# v6 + hgrn workgroups skip gdnpre and run first 16 chain chunks during it (suspend/resume across the barrier)
# baseline (speedup 1.0000x reference)
.Lhs_p3:
	s_movk_i32 s101, 16
	s_cmp_lt_u32 s62, 64
	s_cbranch_scc1 .Lhs_done
	s_sub_u32 s64, s62, 64
	s_movk_i32 s75, 0xc0
